# K LDS-DMA + PV ring + permlane32_swap row-max exchange, WITHOUT the mid-compute V staging (that variant left unconditional V prefetch loads in flight at item exit)
# speedup vs baseline: 1.0068x; 1.0068x over previous
.LBB0_566:
	s_and_saveexec_b64 s[22:23], vcc
	s_cbranch_execz .LBB0_555
	ds_read_b128 v[196:199], v188
	ds_read_b128 v[202:205], v188 offset:32
	ds_read_b128 v[206:209], v188 offset:64
	ds_read_b128 v[210:213], v188 offset:96
	ds_read_b128 v[220:223], v188 offset:128
	ds_read_b128 v[224:227], v188 offset:160
	ds_read_b128 v[2:5], v188 offset:192
	ds_read_b128 v[6:9], v188 offset:224
	s_waitcnt lgkmcnt(7)
	v_mfma_f32_32x32x16_bf16 v[96:111], v[196:199], v[148:151], 0
	ds_read_b128 v[196:199], v188 offset:256
	s_waitcnt lgkmcnt(7)
	v_mfma_f32_32x32x16_bf16 v[96:111], v[202:205], v[144:147], v[96:111]
	ds_read_b128 v[202:205], v188 offset:288
	s_waitcnt lgkmcnt(7)
	v_mfma_f32_32x32x16_bf16 v[96:111], v[206:209], v[140:143], v[96:111]
	ds_read_b128 v[206:209], v188 offset:10752
	s_waitcnt lgkmcnt(7)
	v_mfma_f32_32x32x16_bf16 v[96:111], v[210:213], v[136:139], v[96:111]
	ds_read_b128 v[210:213], v188 offset:10784
	s_waitcnt lgkmcnt(7)
	v_mfma_f32_32x32x16_bf16 v[96:111], v[220:223], v[132:135], v[96:111]
	ds_read_b128 v[220:223], v188 offset:10816
	s_waitcnt lgkmcnt(7)
	v_mfma_f32_32x32x16_bf16 v[96:111], v[224:227], v[128:131], v[96:111]
	ds_read_b128 v[224:227], v188 offset:10848
	s_waitcnt lgkmcnt(7)
	v_mfma_f32_32x32x16_bf16 v[96:111], v[2:5], v[124:127], v[96:111]
	ds_read_b128 v[2:5], v188 offset:10880
	s_waitcnt lgkmcnt(7)
	v_mfma_f32_32x32x16_bf16 v[96:111], v[6:9], v[120:123], v[96:111]
	ds_read_b128 v[6:9], v188 offset:10912
	s_waitcnt lgkmcnt(7)
	v_mfma_f32_32x32x16_bf16 v[96:111], v[196:199], v[116:119], v[96:111]
	ds_read_b128 v[196:199], v188 offset:10944
	s_waitcnt lgkmcnt(7)
	v_mfma_f32_32x32x16_bf16 v[96:111], v[202:205], v[112:115], v[96:111]
	ds_read_b128 v[202:205], v188 offset:10976
	s_waitcnt lgkmcnt(7)
	v_mfma_f32_32x32x16_bf16 v[80:95], v[206:209], v[148:151], 0
	ds_read_b128 v[206:209], v188 offset:11008
	s_waitcnt lgkmcnt(7)
	v_mfma_f32_32x32x16_bf16 v[80:95], v[210:213], v[144:147], v[80:95]
	ds_read_b128 v[210:213], v188 offset:11040
	s_waitcnt lgkmcnt(7)
	v_mfma_f32_32x32x16_bf16 v[80:95], v[220:223], v[140:143], v[80:95]
	s_waitcnt lgkmcnt(6)
	v_mfma_f32_32x32x16_bf16 v[80:95], v[224:227], v[136:139], v[80:95]
	s_waitcnt lgkmcnt(5)
	v_mfma_f32_32x32x16_bf16 v[80:95], v[2:5], v[132:135], v[80:95]
	s_waitcnt lgkmcnt(4)
	v_mfma_f32_32x32x16_bf16 v[80:95], v[6:9], v[128:131], v[80:95]
	s_waitcnt lgkmcnt(3)
	v_mfma_f32_32x32x16_bf16 v[80:95], v[196:199], v[124:127], v[80:95]
	v_max_f32_e32 v0, v97, v97
	v_max_f32_e32 v10, v96, v96
	v_max_f32_e32 v0, v10, v0
	v_max3_f32 v0, v0, v98, v99
	v_max3_f32 v0, v0, v100, v101
	v_max3_f32 v0, v0, v102, v103
	v_max3_f32 v0, v0, v104, v105
	v_max3_f32 v0, v0, v106, v107
	v_max3_f32 v0, v0, v108, v109
	v_max3_f32 v0, v0, v110, v111
	v_and_b32_e32 v3, 64, v218
	v_xor_b32_e32 v2, 32, v218
	v_add_u32_e32 v3, 64, v3
	v_cmp_lt_i32_e64 s[12:13], v2, v3
	s_nop 1
	v_cndmask_b32_e64 v2, v218, v2, s[12:13]
	s_waitcnt lgkmcnt(2)
	v_mfma_f32_32x32x16_bf16 v[80:95], v[202:205], v[120:123], v[80:95]
	s_waitcnt lgkmcnt(1)
	v_mfma_f32_32x32x16_bf16 v[80:95], v[206:209], v[116:119], v[80:95]
	s_waitcnt lgkmcnt(0)
	v_mfma_f32_32x32x16_bf16 v[80:95], v[210:213], v[112:115], v[80:95]
	v_lshlrev_b32_e32 v2, 2, v2
	s_nop 10
	v_max3_f32 v0, v0, v80, v81
	v_max3_f32 v0, v0, v82, v83
	v_max3_f32 v0, v0, v84, v85
	v_max3_f32 v0, v0, v86, v87
	v_max3_f32 v0, v0, v88, v89
	v_max3_f32 v0, v0, v90, v91
	v_max3_f32 v0, v0, v92, v93
	v_max3_f32 v0, v0, v94, v95
	v_mov_b32_e32 v2, v0
	s_nop 1
	v_permlane32_swap_b32_e32 v2, v0
	s_nop 1
	v_add_u32_e32 v224, 0x5000, v194
	v_add_u32_e32 v225, 0x6000, v194
	v_add_u32_e32 v226, 0x7000, v194
	v_add_u32_e32 v227, 0x8000, v194
	ds_read2_b64 v[196:199], v224 offset0:128 offset1:130
	ds_read2_b64 v[202:205], v225 offset0:160 offset1:162
	ds_read2_b64 v[206:209], v226 offset0:192 offset1:194
	ds_read2_b64 v[210:213], v227 offset0:224 offset1:226
	ds_read2_b64 v[220:223], v224 offset0:132 offset1:134
	v_max3_f32 v0, v195, v0, v2
	v_sub_f32 v4, v97, v0
	v_sub_f32 v3, v96, v0
	v_sub_f32 v5, v100, v0
	v_sub_f32_e32 v2, v195, v0
	v_exp_f32_e32 v8, v4
	v_sub_f32 v4, v98, v0
	v_exp_f32_e32 v3, v3
	v_exp_f32_e32 v9, v4
	v_sub_f32 v4, v99, v0
	v_exp_f32_e32 v11, v5
	v_exp_f32_e32 v10, v4
	v_add_f32 v4, v1, v3
	v_sub_f32 v5, v101, v0
	v_exp_f32_e32 v2, v2
	v_add_f32 v4, v4, v8
	v_exp_f32_e32 v12, v5
	v_add_f32 v4, v4, v9
	v_sub_f32 v5, v102, v0
	v_cvt_pk_bf16_f32 v8, v3, v8
	v_add_f32 v4, v4, v10
	v_exp_f32_e32 v13, v5
	v_add_f32 v4, v4, v11
	v_sub_f32 v5, v103, v0
	v_add_f32 v4, v4, v12
	v_exp_f32_e32 v14, v5
	v_add_f32 v4, v4, v13
	v_cvt_pk_bf16_f32 v9, v9, v10
	v_add_f32 v96, v4, v14
	v_sub_f32 v4, v104, v0
	v_exp_f32_e32 v97, v4
	v_sub_f32 v4, v105, v0
	v_cvt_pk_bf16_f32 v10, v11, v12
	v_exp_f32_e32 v98, v4
	v_sub_f32 v4, v106, v0
	v_cvt_pk_bf16_f32 v11, v13, v14
	v_exp_f32_e32 v99, v4
	v_sub_f32 v4, v107, v0
	v_exp_f32_e32 v100, v4
	v_sub_f32 v4, v108, v0
	v_pk_mul_f32 v[64:65], v[64:65], v[2:3] op_sel_hi:[1,0]
	v_pk_mul_f32 v[66:67], v[66:67], v[2:3] op_sel_hi:[1,0]
	v_pk_mul_f32 v[68:69], v[68:69], v[2:3] op_sel_hi:[1,0]
	s_nop 0
	v_exp_f32_e32 v101, v4
	v_sub_f32 v4, v109, v0
	v_pk_mul_f32 v[70:71], v[70:71], v[2:3] op_sel_hi:[1,0]
	v_pk_mul_f32 v[72:73], v[72:73], v[2:3] op_sel_hi:[1,0]
	s_nop 0
	v_exp_f32_e32 v102, v4
	v_sub_f32 v4, v110, v0
	v_pk_mul_f32 v[74:75], v[74:75], v[2:3] op_sel_hi:[1,0]
	v_pk_mul_f32 v[76:77], v[76:77], v[2:3] op_sel_hi:[1,0]
	v_pk_mul_f32 v[78:79], v[78:79], v[2:3] op_sel_hi:[1,0]
	s_nop 0
	v_exp_f32_e32 v103, v4
	s_waitcnt lgkmcnt(4)
	v_mfma_f32_32x32x16_bf16 v[64:79], v[196:199], v[8:11], v[64:79]
	ds_read2_b64 v[196:199], v225 offset0:164 offset1:166
	v_pk_mul_f32 v[48:49], v[48:49], v[2:3] op_sel_hi:[1,0]
	v_pk_mul_f32 v[50:51], v[50:51], v[2:3] op_sel_hi:[1,0]
	v_pk_mul_f32 v[52:53], v[52:53], v[2:3] op_sel_hi:[1,0]
	v_pk_mul_f32 v[54:55], v[54:55], v[2:3] op_sel_hi:[1,0]
	v_pk_mul_f32 v[56:57], v[56:57], v[2:3] op_sel_hi:[1,0]
	v_pk_mul_f32 v[58:59], v[58:59], v[2:3] op_sel_hi:[1,0]
	v_pk_mul_f32 v[60:61], v[60:61], v[2:3] op_sel_hi:[1,0]
	v_pk_mul_f32 v[62:63], v[62:63], v[2:3] op_sel_hi:[1,0]
	s_waitcnt lgkmcnt(4)
	v_mfma_f32_32x32x16_bf16 v[48:63], v[202:205], v[8:11], v[48:63]
	ds_read2_b64 v[202:205], v226 offset0:196 offset1:198
	v_pk_mul_f32 v[32:33], v[32:33], v[2:3] op_sel_hi:[1,0]
	v_pk_mul_f32 v[34:35], v[34:35], v[2:3] op_sel_hi:[1,0]
	v_pk_mul_f32 v[36:37], v[36:37], v[2:3] op_sel_hi:[1,0]
	v_pk_mul_f32 v[38:39], v[38:39], v[2:3] op_sel_hi:[1,0]
	v_pk_mul_f32 v[40:41], v[40:41], v[2:3] op_sel_hi:[1,0]
	v_pk_mul_f32 v[42:43], v[42:43], v[2:3] op_sel_hi:[1,0]
	v_pk_mul_f32 v[44:45], v[44:45], v[2:3] op_sel_hi:[1,0]
	v_pk_mul_f32 v[46:47], v[46:47], v[2:3] op_sel_hi:[1,0]
	v_pk_mul_f32 v[16:17], v[16:17], v[2:3] op_sel_hi:[1,0]
	v_pk_mul_f32 v[18:19], v[18:19], v[2:3] op_sel_hi:[1,0]
	v_pk_mul_f32 v[20:21], v[20:21], v[2:3] op_sel_hi:[1,0]
	s_waitcnt lgkmcnt(4)
	v_mfma_f32_32x32x16_bf16 v[32:47], v[206:209], v[8:11], v[32:47]
	ds_read2_b64 v[206:209], v227 offset0:228 offset1:230
	v_pk_mul_f32 v[22:23], v[22:23], v[2:3] op_sel_hi:[1,0]
	v_pk_mul_f32 v[24:25], v[24:25], v[2:3] op_sel_hi:[1,0]
	v_pk_mul_f32 v[26:27], v[26:27], v[2:3] op_sel_hi:[1,0]
	v_pk_mul_f32 v[28:29], v[28:29], v[2:3] op_sel_hi:[1,0]
	v_pk_mul_f32 v[30:31], v[30:31], v[2:3] op_sel_hi:[1,0]
	v_mov_b32_e32 v195, v0
	s_waitcnt lgkmcnt(4)
	v_mfma_f32_32x32x16_bf16 v[16:31], v[210:213], v[8:11], v[16:31]
	ds_read2_b64 v[210:213], v224 offset0:136 offset1:138
	v_sub_f32 v8, v111, v0
	v_cvt_pk_bf16_f32 v9, v99, v100
	v_exp_f32_e32 v107, v8
	v_cvt_pk_bf16_f32 v8, v97, v98
	v_cvt_pk_bf16_f32 v10, v101, v102
	v_cvt_pk_bf16_f32 v11, v103, v107
	s_nop 0
	s_waitcnt lgkmcnt(4)
	v_mfma_f32_32x32x16_bf16 v[64:79], v[220:223], v[8:11], v[64:79]
	ds_read2_b64 v[220:223], v225 offset0:168 offset1:170
	v_add_f32 v4, v96, v97
	s_nop 0
	v_add_f32 v4, v4, v98
	s_nop 0
	v_add_f32 v4, v4, v99
	s_nop 0
	v_add_f32 v96, v4, v100
	v_sub_f32 v4, v80, v0
	s_waitcnt lgkmcnt(4)
	v_mfma_f32_32x32x16_bf16 v[48:63], v[196:199], v[8:11], v[48:63]
	ds_read2_b64 v[196:199], v226 offset0:200 offset1:202
	v_exp_f32_e32 v80, v4
	v_sub_f32 v12, v81, v0
	s_nop 0
	v_exp_f32_e32 v81, v12
	v_sub_f32 v12, v82, v0
	s_nop 0
	v_exp_f32_e32 v82, v12
	v_sub_f32 v12, v83, v0
	s_waitcnt lgkmcnt(4)
	v_mfma_f32_32x32x16_bf16 v[32:47], v[202:205], v[8:11], v[32:47]
	ds_read2_b64 v[202:205], v227 offset0:232 offset1:234
	v_exp_f32_e32 v83, v12
	v_sub_f32 v4, v84, v0
	s_nop 0
	v_exp_f32_e32 v84, v4
	v_sub_f32 v4, v85, v0
	s_nop 0
	v_exp_f32_e32 v85, v4
	v_sub_f32 v4, v86, v0
	s_waitcnt lgkmcnt(4)
	v_mfma_f32_32x32x16_bf16 v[16:31], v[206:209], v[8:11], v[16:31]
	ds_read2_b64 v[206:209], v224 offset0:140 offset1:142
	v_exp_f32_e32 v86, v4
	v_sub_f32 v8, v87, v0
	v_exp_f32_e32 v87, v8
	v_cvt_pk_bf16_f32 v8, v80, v81
	v_cvt_pk_bf16_f32 v9, v82, v83
	v_cvt_pk_bf16_f32 v10, v84, v85
	v_cvt_pk_bf16_f32 v11, v86, v87
	s_nop 0
	s_waitcnt lgkmcnt(4)
	v_mfma_f32_32x32x16_bf16 v[64:79], v[210:213], v[8:11], v[64:79]
	ds_read2_b64 v[210:213], v225 offset0:172 offset1:174
	v_add_f32 v4, v96, v101
	s_nop 0
	v_add_f32 v4, v4, v102
	s_nop 0
	v_add_f32 v4, v4, v103
	s_nop 0
	v_add_f32 v96, v4, v107
	v_sub_f32 v4, v88, v0
	s_waitcnt lgkmcnt(4)
	v_mfma_f32_32x32x16_bf16 v[48:63], v[220:223], v[8:11], v[48:63]
	ds_read2_b64 v[220:223], v226 offset0:204 offset1:206
	v_exp_f32_e32 v88, v4
	v_sub_f32 v12, v89, v0
	s_nop 0
	v_exp_f32_e32 v89, v12
	v_sub_f32 v12, v90, v0
	s_nop 0
	v_exp_f32_e32 v90, v12
	v_sub_f32 v12, v91, v0
	s_waitcnt lgkmcnt(4)
	v_mfma_f32_32x32x16_bf16 v[32:47], v[196:199], v[8:11], v[32:47]
	ds_read2_b64 v[196:199], v227 offset0:236 offset1:238
	v_exp_f32_e32 v91, v12
	v_sub_f32 v4, v92, v0
	s_nop 0
	v_exp_f32_e32 v92, v4
	v_sub_f32 v4, v93, v0
	s_nop 0
	v_exp_f32_e32 v93, v4
	v_sub_f32 v4, v94, v0
	s_waitcnt lgkmcnt(4)
	v_mfma_f32_32x32x16_bf16 v[16:31], v[202:205], v[8:11], v[16:31]
	v_exp_f32_e32 v94, v4
	v_sub_f32 v8, v95, v0
	v_cvt_pk_bf16_f32 v9, v90, v91
	v_exp_f32_e32 v95, v8
	v_cvt_pk_bf16_f32 v8, v88, v89
	v_cvt_pk_bf16_f32 v10, v92, v93
	v_add_f32 v3, v96, v80
	v_cvt_pk_bf16_f32 v11, v94, v95
	v_add_f32 v3, v3, v81
	s_nop 0
	v_add_f32 v3, v3, v82
	s_waitcnt lgkmcnt(3)
	v_mfma_f32_32x32x16_bf16 v[64:79], v[206:209], v[8:11], v[64:79]
	v_add_f32 v3, v3, v83
	s_nop 0
	v_add_f32 v3, v3, v84
	s_nop 0
	v_add_f32 v3, v3, v85
	s_waitcnt lgkmcnt(2)
	v_mfma_f32_32x32x16_bf16 v[48:63], v[210:213], v[8:11], v[48:63]
	v_add_f32 v3, v3, v86
	s_nop 0
	v_add_f32 v3, v3, v87
	s_nop 0
	v_add_f32 v3, v3, v88
	s_nop 0
	v_add_f32 v3, v3, v89
	s_waitcnt lgkmcnt(1)
	v_mfma_f32_32x32x16_bf16 v[32:47], v[220:223], v[8:11], v[32:47]
	v_add_f32 v3, v3, v90
	s_nop 0
	v_add_f32 v3, v3, v91
	s_nop 0
	v_add_f32 v3, v3, v92
	s_nop 0
	v_add_f32 v3, v3, v93
	s_waitcnt lgkmcnt(0)
	v_mfma_f32_32x32x16_bf16 v[16:31], v[196:199], v[8:11], v[16:31]
	v_add_f32 v3, v3, v94
	s_nop 0
	v_add_f32 v3, v3, v95
	s_nop 0
	v_fmac_f32_e32 v3, v184, v2
	v_mov_b32_e32 v184, v3
	s_branch .LBB0_555
